# prompt-MLA step: 12 K-fragment LDS reads issued up front with counted waits, lean v_max3 tree, PV transposed reads prefetched ahead of the exp section
# speedup vs baseline: 1.0103x; 1.0103x over previous
.LBB0_1165:
	s_sub_i32 s45, s42, 64
	s_cmp_ge_u32 s45, s66
	s_cselect_b64 s[48:49], -1, 0
	s_cmp_gt_i32 s44, s39
	s_cselect_b64 s[50:51], -1, 0
	s_or_b64 s[48:49], s[50:51], s[48:49]
	s_and_b64 vcc, exec, s[48:49]
	s_cbranch_vccnz .LBB0_1169
	v_add_u32_e32 v120, v124, v198
	ds_read_b128 v[136:139], v120
	ds_read_b128 v[140:143], v120 offset:6656
	ds_read_b128 v[144:147], v120 offset:32
	ds_read_b128 v[148:151], v120 offset:6688
	ds_read_b128 v[152:155], v120 offset:64
	ds_read_b128 v[156:159], v120 offset:6720
	ds_read_b128 v[160:163], v120 offset:96
	ds_read_b128 v[164:167], v120 offset:6752
	ds_read_b128 v[168:171], v120 offset:128
	ds_read_b128 v[172:175], v120 offset:6784
	ds_read_b128 v[176:179], v120 offset:160
	ds_read_b128 v[180:183], v120 offset:6816
	v_add_u32_e32 v184, v125, v126
	s_waitcnt lgkmcnt(11)
	v_mfma_f32_32x32x16_bf16 v[34:49], v[136:139], v[66:69], 0
	s_waitcnt lgkmcnt(10)
	v_mfma_f32_32x32x16_bf16 v[50:65], v[140:143], v[66:69], 0
	s_waitcnt lgkmcnt(9)
	v_mfma_f32_32x32x16_bf16 v[34:49], v[144:147], v[70:73], v[34:49]
	s_waitcnt lgkmcnt(8)
	v_mfma_f32_32x32x16_bf16 v[50:65], v[148:151], v[70:73], v[50:65]
	s_waitcnt lgkmcnt(7)
	v_mfma_f32_32x32x16_bf16 v[34:49], v[152:155], v[74:77], v[34:49]
	s_waitcnt lgkmcnt(6)
	v_mfma_f32_32x32x16_bf16 v[50:65], v[156:159], v[74:77], v[50:65]
	s_waitcnt lgkmcnt(5)
	v_mfma_f32_32x32x16_bf16 v[34:49], v[160:163], v[78:81], v[34:49]
	s_waitcnt lgkmcnt(4)
	v_mfma_f32_32x32x16_bf16 v[50:65], v[164:167], v[78:81], v[50:65]
	s_waitcnt lgkmcnt(3)
	v_mfma_f32_32x32x16_bf16 v[34:49], v[168:171], v[106:109], v[34:49]
	s_waitcnt lgkmcnt(2)
	v_mfma_f32_32x32x16_bf16 v[50:65], v[172:175], v[106:109], v[50:65]
	s_waitcnt lgkmcnt(1)
	v_mfma_f32_32x32x16_bf16 v[34:49], v[176:179], v[110:113], v[34:49]
	s_waitcnt lgkmcnt(0)
	v_mfma_f32_32x32x16_bf16 v[50:65], v[180:183], v[110:113], v[50:65]
	s_nop 11
	v_max3_f32 v120, v34, v35, v36
	v_max3_f32 v120, v120, v37, v38
	v_max3_f32 v120, v120, v39, v40
	v_max3_f32 v120, v120, v41, v42
	v_max3_f32 v120, v120, v43, v44
	v_max3_f32 v120, v120, v45, v46
	v_max3_f32 v120, v120, v47, v48
	v_max3_f32 v120, v120, v49, v50
	v_max3_f32 v120, v120, v51, v52
	v_max3_f32 v120, v120, v53, v54
	v_max3_f32 v120, v120, v55, v56
	v_max3_f32 v120, v120, v57, v58
	v_max3_f32 v120, v120, v59, v60
	v_max3_f32 v120, v120, v61, v62
	v_max3_f32 v120, v120, v63, v64
	v_max_f32_e32 v120, v120, v65
	v_and_b32_e32 v131, 64, v218
	v_xor_b32_e32 v130, 32, v218
	v_add_u32_e32 v131, 64, v131
	v_cmp_lt_i32_e32 vcc, v130, v131
	s_nop 1
	v_cndmask_b32_e32 v130, v218, v130, vcc
	v_lshlrev_b32_e32 v130, 2, v130
	ds_bpermute_b32 v130, v130, v120
	s_waitcnt lgkmcnt(0)
	ds_read_b64_tr_b16 v[136:137], v184 offset:13312
	ds_read_b64_tr_b16 v[138:139], v184 offset:14464
	ds_read_b64_tr_b16 v[140:141], v184 offset:13376
	ds_read_b64_tr_b16 v[142:143], v184 offset:14528
	ds_read_b64_tr_b16 v[144:145], v184 offset:15616
	ds_read_b64_tr_b16 v[146:147], v184 offset:16768
	ds_read_b64_tr_b16 v[148:149], v184 offset:15680
	ds_read_b64_tr_b16 v[150:151], v184 offset:16832
	ds_read_b64_tr_b16 v[152:153], v184 offset:17920
	ds_read_b64_tr_b16 v[154:155], v184 offset:19072
	ds_read_b64_tr_b16 v[156:157], v184 offset:17984
	ds_read_b64_tr_b16 v[158:159], v184 offset:19136
	ds_read_b64_tr_b16 v[160:161], v184 offset:20224
	ds_read_b64_tr_b16 v[162:163], v184 offset:21376
	ds_read_b64_tr_b16 v[164:165], v184 offset:20288
	ds_read_b64_tr_b16 v[166:167], v184 offset:21440
	v_max3_f32 v130, v129, v120, v130
	v_sub_f32_e32 v120, v129, v130
	v_exp_f32_e32 v120, v120
	s_nop 0
	v_cmp_neq_f32_e32 vcc, 1.0, v120
	s_cbranch_vccz .LBB0_1168
	v_pk_mul_f32 v[16:17], v[16:17], v[120:121] op_sel_hi:[1,0]
	v_pk_mul_f32 v[14:15], v[14:15], v[120:121] op_sel_hi:[1,0]
	v_pk_mul_f32 v[12:13], v[12:13], v[120:121] op_sel_hi:[1,0]
	v_pk_mul_f32 v[10:11], v[10:11], v[120:121] op_sel_hi:[1,0]
	v_pk_mul_f32 v[8:9], v[8:9], v[120:121] op_sel_hi:[1,0]
	v_pk_mul_f32 v[6:7], v[6:7], v[120:121] op_sel_hi:[1,0]
	v_pk_mul_f32 v[4:5], v[4:5], v[120:121] op_sel_hi:[1,0]
	v_pk_mul_f32 v[2:3], v[2:3], v[120:121] op_sel_hi:[1,0]
	v_pk_mul_f32 v[32:33], v[32:33], v[120:121] op_sel_hi:[1,0]
	v_pk_mul_f32 v[30:31], v[30:31], v[120:121] op_sel_hi:[1,0]
	v_pk_mul_f32 v[28:29], v[28:29], v[120:121] op_sel_hi:[1,0]
	v_pk_mul_f32 v[26:27], v[26:27], v[120:121] op_sel_hi:[1,0]
	v_pk_mul_f32 v[24:25], v[24:25], v[120:121] op_sel_hi:[1,0]
	v_pk_mul_f32 v[22:23], v[22:23], v[120:121] op_sel_hi:[1,0]
	v_pk_mul_f32 v[20:21], v[20:21], v[120:121] op_sel_hi:[1,0]
	v_pk_mul_f32 v[18:19], v[18:19], v[120:121] op_sel_hi:[1,0]
.LBB0_1168:
	v_sub_f32_e32 v34, v34, v130
	v_sub_f32_e32 v50, v50, v130
	v_exp_f32_e32 v34, v34
	v_exp_f32_e32 v50, v50
	v_sub_f32_e32 v35, v35, v130
	v_sub_f32_e32 v51, v51, v130
	v_exp_f32_e32 v35, v35
	v_exp_f32_e32 v51, v51
	v_sub_f32_e32 v36, v36, v130
	v_sub_f32_e32 v52, v52, v130
	v_exp_f32_e32 v36, v36
	v_exp_f32_e32 v52, v52
	v_sub_f32_e32 v37, v37, v130
	v_sub_f32_e32 v53, v53, v130
	v_exp_f32_e32 v37, v37
	v_exp_f32_e32 v53, v53
	v_sub_f32_e32 v38, v38, v130
	v_sub_f32_e32 v54, v54, v130
	v_add_f32_e32 v129, v34, v50
	v_exp_f32_e32 v38, v38
	v_exp_f32_e32 v54, v54
	v_sub_f32_e32 v39, v39, v130
	v_sub_f32_e32 v55, v55, v130
	v_add_f32_e32 v129, 0, v129
	v_add_f32_e32 v131, v35, v51
	v_exp_f32_e32 v39, v39
	v_exp_f32_e32 v55, v55
	v_sub_f32_e32 v40, v40, v130
	v_sub_f32_e32 v56, v56, v130
	v_add_f32_e32 v129, v131, v129
	v_add_f32_e32 v131, v36, v52
	v_exp_f32_e32 v40, v40
	v_exp_f32_e32 v56, v56
	v_sub_f32_e32 v41, v41, v130
	v_sub_f32_e32 v57, v57, v130
	v_add_f32_e32 v129, v131, v129
	v_add_f32_e32 v131, v37, v53
	v_exp_f32_e32 v41, v41
	v_exp_f32_e32 v57, v57
	v_sub_f32_e32 v42, v42, v130
	v_sub_f32_e32 v58, v58, v130
	v_add_f32_e32 v129, v131, v129
	v_add_f32_e32 v131, v38, v54
	v_exp_f32_e32 v42, v42
	v_exp_f32_e32 v58, v58
	v_sub_f32_e32 v43, v43, v130
	v_sub_f32_e32 v59, v59, v130
	v_add_f32_e32 v129, v131, v129
	v_add_f32_e32 v131, v39, v55
	v_exp_f32_e32 v43, v43
	v_exp_f32_e32 v59, v59
	v_sub_f32_e32 v44, v44, v130
	v_sub_f32_e32 v60, v60, v130
	v_add_f32_e32 v129, v131, v129
	v_add_f32_e32 v131, v40, v56
	v_exp_f32_e32 v44, v44
	v_exp_f32_e32 v60, v60
	v_sub_f32_e32 v45, v45, v130
	v_sub_f32_e32 v61, v61, v130
	v_add_f32_e32 v129, v131, v129
	v_add_f32_e32 v131, v41, v57
	v_exp_f32_e32 v45, v45
	v_exp_f32_e32 v61, v61
	v_add_f32_e32 v129, v131, v129
	v_add_f32_e32 v131, v42, v58
	v_add_f32_e32 v129, v131, v129
	v_add_f32_e32 v131, v43, v59
	v_add_f32_e32 v129, v131, v129
	v_add_f32_e32 v131, v44, v60
	v_add_f32_e32 v129, v131, v129
	v_add_f32_e32 v131, v45, v61
	v_sub_f32_e32 v46, v46, v130
	v_add_f32_e32 v129, v131, v129
	v_exp_f32_e32 v131, v46
	v_sub_f32_e32 v46, v62, v130
	v_exp_f32_e32 v62, v46
	v_sub_f32_e32 v47, v47, v130
	v_cvt_pk_bf16_f32 v42, v42, v43
	v_cvt_pk_bf16_f32 v43, v44, v45
	v_add_f32_e32 v46, v131, v62
	v_add_f32_e32 v46, v46, v129
	v_exp_f32_e32 v129, v47
	v_sub_f32_e32 v47, v63, v130
	v_exp_f32_e32 v63, v47
	v_cvt_pk_bf16_f32 v44, v131, v129
	v_add_f32_e32 v47, v129, v63
	v_add_f32_e32 v46, v47, v46
	v_sub_f32_e32 v47, v48, v130
	v_exp_f32_e32 v132, v47
	v_sub_f32_e32 v47, v64, v130
	v_exp_f32_e32 v64, v47
	v_cvt_pk_bf16_f32 v48, v38, v39
	v_cvt_pk_bf16_f32 v38, v50, v51
	v_cvt_pk_bf16_f32 v39, v52, v53
	v_add_f32_e32 v47, v132, v64
	v_add_f32_e32 v46, v47, v46
	v_sub_f32_e32 v47, v49, v130
	v_exp_f32_e32 v133, v47
	v_sub_f32_e32 v47, v65, v130
	v_exp_f32_e32 v65, v47
	v_cvt_pk_bf16_f32 v49, v40, v41
	v_cvt_pk_bf16_f32 v40, v54, v55
	v_cvt_pk_bf16_f32 v41, v56, v57
	v_add_f32_e32 v47, v133, v65
	v_add_f32_e32 v134, v47, v46
	v_cvt_pk_bf16_f32 v46, v34, v35
	v_cvt_pk_bf16_f32 v34, v58, v59
	v_cvt_pk_bf16_f32 v47, v36, v37
	v_cvt_pk_bf16_f32 v45, v132, v133
	v_cvt_pk_bf16_f32 v35, v60, v61
	s_waitcnt lgkmcnt(0)
	v_mfma_f32_32x32x16_bf16 v[2:17], v[136:139], v[46:49], v[2:17]
	v_cvt_pk_bf16_f32 v36, v62, v63
	v_cvt_pk_bf16_f32 v37, v64, v65
	v_fmac_f32_e32 v134, v128, v120
	v_mov_b32_e32 v128, v134
	v_mfma_f32_32x32x16_bf16 v[18:33], v[140:143], v[46:49], v[18:33]
	v_mfma_f32_32x32x16_bf16 v[2:17], v[144:147], v[42:45], v[2:17]
	v_mfma_f32_32x32x16_bf16 v[18:33], v[148:151], v[42:45], v[18:33]
	v_mfma_f32_32x32x16_bf16 v[2:17], v[152:155], v[38:41], v[2:17]
	v_mfma_f32_32x32x16_bf16 v[18:33], v[156:159], v[38:41], v[18:33]
	v_mfma_f32_32x32x16_bf16 v[2:17], v[160:163], v[34:37], v[2:17]
	v_mfma_f32_32x32x16_bf16 v[18:33], v[164:167], v[34:37], v[18:33]
	s_branch .LBB0_1170

.LBB0_1179:
	s_cmp_ge_u32 s42, s66
	s_cselect_b64 s[48:49], -1, 0
	s_cmp_ge_i32 s44, s39
	s_cselect_b64 s[50:51], -1, 0
	s_or_b64 s[48:49], s[50:51], s[48:49]
	s_and_b64 vcc, exec, s[48:49]
	s_cbranch_vccnz .LBB0_1184
	v_add_u32_e32 v120, v124, v198
	ds_read_b128 v[136:139], v120 offset:32768
	ds_read_b128 v[140:143], v120 offset:39424
	ds_read_b128 v[144:147], v120 offset:32800
	ds_read_b128 v[148:151], v120 offset:39456
	ds_read_b128 v[152:155], v120 offset:32832
	ds_read_b128 v[156:159], v120 offset:39488
	ds_read_b128 v[160:163], v120 offset:32864
	ds_read_b128 v[164:167], v120 offset:39520
	ds_read_b128 v[168:171], v120 offset:32896
	ds_read_b128 v[172:175], v120 offset:39552
	ds_read_b128 v[176:179], v120 offset:32928
	ds_read_b128 v[180:183], v120 offset:39584
	v_add_u32_e32 v184, v125, v126
	s_waitcnt lgkmcnt(11)
	v_mfma_f32_32x32x16_bf16 v[34:49], v[136:139], v[66:69], 0
	s_waitcnt lgkmcnt(10)
	v_mfma_f32_32x32x16_bf16 v[50:65], v[140:143], v[66:69], 0
	s_waitcnt lgkmcnt(9)
	v_mfma_f32_32x32x16_bf16 v[34:49], v[144:147], v[70:73], v[34:49]
	s_waitcnt lgkmcnt(8)
	v_mfma_f32_32x32x16_bf16 v[50:65], v[148:151], v[70:73], v[50:65]
	s_waitcnt lgkmcnt(7)
	v_mfma_f32_32x32x16_bf16 v[34:49], v[152:155], v[74:77], v[34:49]
	s_waitcnt lgkmcnt(6)
	v_mfma_f32_32x32x16_bf16 v[50:65], v[156:159], v[74:77], v[50:65]
	s_waitcnt lgkmcnt(5)
	v_mfma_f32_32x32x16_bf16 v[34:49], v[160:163], v[78:81], v[34:49]
	s_waitcnt lgkmcnt(4)
	v_mfma_f32_32x32x16_bf16 v[50:65], v[164:167], v[78:81], v[50:65]
	s_waitcnt lgkmcnt(3)
	v_mfma_f32_32x32x16_bf16 v[34:49], v[168:171], v[106:109], v[34:49]
	s_waitcnt lgkmcnt(2)
	v_mfma_f32_32x32x16_bf16 v[50:65], v[172:175], v[106:109], v[50:65]
	s_waitcnt lgkmcnt(1)
	v_mfma_f32_32x32x16_bf16 v[34:49], v[176:179], v[110:113], v[34:49]
	s_waitcnt lgkmcnt(0)
	v_mfma_f32_32x32x16_bf16 v[50:65], v[180:183], v[110:113], v[50:65]
	s_nop 11
	v_max3_f32 v120, v34, v35, v36
	v_max3_f32 v120, v120, v37, v38
	v_max3_f32 v120, v120, v39, v40
	v_max3_f32 v120, v120, v41, v42
	v_max3_f32 v120, v120, v43, v44
	v_max3_f32 v120, v120, v45, v46
	v_max3_f32 v120, v120, v47, v48
	v_max3_f32 v120, v120, v49, v50
	v_max3_f32 v120, v120, v51, v52
	v_max3_f32 v120, v120, v53, v54
	v_max3_f32 v120, v120, v55, v56
	v_max3_f32 v120, v120, v57, v58
	v_max3_f32 v120, v120, v59, v60
	v_max3_f32 v120, v120, v61, v62
	v_max3_f32 v120, v120, v63, v64
	v_max_f32_e32 v120, v120, v65
	v_and_b32_e32 v131, 64, v218
	v_xor_b32_e32 v129, 32, v218
	v_add_u32_e32 v131, 64, v131
	v_cmp_lt_i32_e32 vcc, v129, v131
	s_nop 1
	v_cndmask_b32_e32 v129, v218, v129, vcc
	v_lshlrev_b32_e32 v129, 2, v129
	ds_bpermute_b32 v129, v129, v120
	s_waitcnt lgkmcnt(0)
	ds_read_b64_tr_b16 v[136:137], v184 offset:46080
	ds_read_b64_tr_b16 v[138:139], v184 offset:47232
	ds_read_b64_tr_b16 v[140:141], v184 offset:46144
	ds_read_b64_tr_b16 v[142:143], v184 offset:47296
	ds_read_b64_tr_b16 v[144:145], v184 offset:48384
	ds_read_b64_tr_b16 v[146:147], v184 offset:49536
	ds_read_b64_tr_b16 v[148:149], v184 offset:48448
	ds_read_b64_tr_b16 v[150:151], v184 offset:49600
	ds_read_b64_tr_b16 v[152:153], v184 offset:50688
	ds_read_b64_tr_b16 v[154:155], v184 offset:51840
	ds_read_b64_tr_b16 v[156:157], v184 offset:50752
	ds_read_b64_tr_b16 v[158:159], v184 offset:51904
	ds_read_b64_tr_b16 v[160:161], v184 offset:52992
	ds_read_b64_tr_b16 v[162:163], v184 offset:54144
	ds_read_b64_tr_b16 v[164:165], v184 offset:53056
	ds_read_b64_tr_b16 v[166:167], v184 offset:54208
	v_max3_f32 v129, v130, v120, v129
	v_sub_f32_e32 v120, v130, v129
	v_exp_f32_e32 v120, v120
	s_nop 0
	v_cmp_neq_f32_e32 vcc, 1.0, v120
	s_cbranch_vccz .LBB0_1182
	v_pk_mul_f32 v[16:17], v[16:17], v[120:121] op_sel_hi:[1,0]
	v_pk_mul_f32 v[14:15], v[14:15], v[120:121] op_sel_hi:[1,0]
	v_pk_mul_f32 v[12:13], v[12:13], v[120:121] op_sel_hi:[1,0]
	v_pk_mul_f32 v[10:11], v[10:11], v[120:121] op_sel_hi:[1,0]
	v_pk_mul_f32 v[8:9], v[8:9], v[120:121] op_sel_hi:[1,0]
	v_pk_mul_f32 v[6:7], v[6:7], v[120:121] op_sel_hi:[1,0]
	v_pk_mul_f32 v[4:5], v[4:5], v[120:121] op_sel_hi:[1,0]
	v_pk_mul_f32 v[2:3], v[2:3], v[120:121] op_sel_hi:[1,0]
	v_pk_mul_f32 v[32:33], v[32:33], v[120:121] op_sel_hi:[1,0]
	v_pk_mul_f32 v[30:31], v[30:31], v[120:121] op_sel_hi:[1,0]
	v_pk_mul_f32 v[28:29], v[28:29], v[120:121] op_sel_hi:[1,0]
	v_pk_mul_f32 v[26:27], v[26:27], v[120:121] op_sel_hi:[1,0]
	v_pk_mul_f32 v[24:25], v[24:25], v[120:121] op_sel_hi:[1,0]
	v_pk_mul_f32 v[22:23], v[22:23], v[120:121] op_sel_hi:[1,0]
	v_pk_mul_f32 v[20:21], v[20:21], v[120:121] op_sel_hi:[1,0]
	v_pk_mul_f32 v[18:19], v[18:19], v[120:121] op_sel_hi:[1,0]
.LBB0_1182:
	v_sub_f32_e32 v34, v34, v129
	v_sub_f32_e32 v50, v50, v129
	v_exp_f32_e32 v34, v34
	v_exp_f32_e32 v50, v50
	v_sub_f32_e32 v35, v35, v129
	v_sub_f32_e32 v51, v51, v129
	v_exp_f32_e32 v35, v35
	v_exp_f32_e32 v51, v51
	v_sub_f32_e32 v36, v36, v129
	v_sub_f32_e32 v52, v52, v129
	v_exp_f32_e32 v36, v36
	v_exp_f32_e32 v52, v52
	v_sub_f32_e32 v37, v37, v129
	v_sub_f32_e32 v53, v53, v129
	v_exp_f32_e32 v37, v37
	v_exp_f32_e32 v53, v53
	v_sub_f32_e32 v38, v38, v129
	v_sub_f32_e32 v54, v54, v129
	v_add_f32_e32 v130, v34, v50
	v_exp_f32_e32 v38, v38
	v_exp_f32_e32 v54, v54
	v_sub_f32_e32 v39, v39, v129
	v_sub_f32_e32 v55, v55, v129
	v_add_f32_e32 v130, 0, v130
	v_add_f32_e32 v131, v35, v51
	v_exp_f32_e32 v39, v39
	v_exp_f32_e32 v55, v55
	v_sub_f32_e32 v40, v40, v129
	v_sub_f32_e32 v56, v56, v129
	v_add_f32_e32 v130, v131, v130
	v_add_f32_e32 v131, v36, v52
	v_exp_f32_e32 v40, v40
	v_exp_f32_e32 v56, v56
	v_sub_f32_e32 v41, v41, v129
	v_sub_f32_e32 v57, v57, v129
	v_add_f32_e32 v130, v131, v130
	v_add_f32_e32 v131, v37, v53
	v_exp_f32_e32 v41, v41
	v_exp_f32_e32 v57, v57
	v_sub_f32_e32 v42, v42, v129
	v_sub_f32_e32 v58, v58, v129
	v_add_f32_e32 v130, v131, v130
	v_add_f32_e32 v131, v38, v54
	v_exp_f32_e32 v42, v42
	v_exp_f32_e32 v58, v58
	v_sub_f32_e32 v43, v43, v129
	v_sub_f32_e32 v59, v59, v129
	v_add_f32_e32 v130, v131, v130
	v_add_f32_e32 v131, v39, v55
	v_exp_f32_e32 v43, v43
	v_exp_f32_e32 v59, v59
	v_sub_f32_e32 v44, v44, v129
	v_sub_f32_e32 v60, v60, v129
	v_add_f32_e32 v130, v131, v130
	v_add_f32_e32 v131, v40, v56
	v_exp_f32_e32 v44, v44
	v_exp_f32_e32 v60, v60
	v_sub_f32_e32 v45, v45, v129
	v_sub_f32_e32 v61, v61, v129
	v_add_f32_e32 v130, v131, v130
	v_add_f32_e32 v131, v41, v57
	v_exp_f32_e32 v45, v45
	v_exp_f32_e32 v61, v61
	v_add_f32_e32 v130, v131, v130
	v_add_f32_e32 v131, v42, v58
	v_add_f32_e32 v130, v131, v130
	v_add_f32_e32 v131, v43, v59
	v_add_f32_e32 v130, v131, v130
	v_add_f32_e32 v131, v44, v60
	v_add_f32_e32 v130, v131, v130
	v_add_f32_e32 v131, v45, v61
	v_sub_f32_e32 v46, v46, v129
	v_add_f32_e32 v130, v131, v130
	v_exp_f32_e32 v131, v46
	v_sub_f32_e32 v46, v62, v129
	v_exp_f32_e32 v62, v46
	v_sub_f32_e32 v47, v47, v129
	v_cvt_pk_bf16_f32 v42, v42, v43
	v_cvt_pk_bf16_f32 v43, v44, v45
	v_add_f32_e32 v46, v131, v62
	v_add_f32_e32 v46, v46, v130
	v_exp_f32_e32 v130, v47
	v_sub_f32_e32 v47, v63, v129
	v_exp_f32_e32 v63, v47
	v_cvt_pk_bf16_f32 v44, v131, v130
	v_add_f32_e32 v47, v130, v63
	v_add_f32_e32 v46, v47, v46
	v_sub_f32_e32 v47, v48, v129
	v_exp_f32_e32 v132, v47
	v_sub_f32_e32 v47, v64, v129
	v_exp_f32_e32 v64, v47
	v_cvt_pk_bf16_f32 v48, v38, v39
	v_cvt_pk_bf16_f32 v38, v50, v51
	v_cvt_pk_bf16_f32 v39, v52, v53
	v_add_f32_e32 v47, v132, v64
	v_add_f32_e32 v46, v47, v46
	v_sub_f32_e32 v47, v49, v129
	v_exp_f32_e32 v133, v47
	v_sub_f32_e32 v47, v65, v129
	v_exp_f32_e32 v65, v47
	v_cvt_pk_bf16_f32 v49, v40, v41
	v_cvt_pk_bf16_f32 v40, v54, v55
	v_cvt_pk_bf16_f32 v41, v56, v57
	v_add_f32_e32 v47, v133, v65
	v_add_f32_e32 v134, v47, v46
	v_cvt_pk_bf16_f32 v46, v34, v35
	v_cvt_pk_bf16_f32 v34, v58, v59
	v_cvt_pk_bf16_f32 v47, v36, v37
	v_cvt_pk_bf16_f32 v45, v132, v133
	v_cvt_pk_bf16_f32 v35, v60, v61
	s_waitcnt lgkmcnt(0)
	v_mfma_f32_32x32x16_bf16 v[2:17], v[136:139], v[46:49], v[2:17]
	v_cvt_pk_bf16_f32 v36, v62, v63
	v_cvt_pk_bf16_f32 v37, v64, v65
	v_fmac_f32_e32 v134, v128, v120
	v_mov_b32_e32 v128, v134
	v_mfma_f32_32x32x16_bf16 v[18:33], v[140:143], v[46:49], v[18:33]
	v_mfma_f32_32x32x16_bf16 v[2:17], v[144:147], v[42:45], v[2:17]
	v_mfma_f32_32x32x16_bf16 v[18:33], v[148:151], v[42:45], v[18:33]
	v_mfma_f32_32x32x16_bf16 v[2:17], v[152:155], v[38:41], v[2:17]
	v_mfma_f32_32x32x16_bf16 v[18:33], v[156:159], v[38:41], v[18:33]
	v_mfma_f32_32x32x16_bf16 v[2:17], v[160:163], v[34:37], v[2:17]
	v_mfma_f32_32x32x16_bf16 v[18:33], v[164:167], v[34:37], v[18:33]
	s_cmp_ge_u32 s44, s38
	s_cbranch_scc0 .LBB0_1185
	s_branch .LBB0_1188
